# sparse attention: no wave priority raise around the MFMA bursts (lets the partner wave's vector work interleave)
# baseline (speedup 1.0000x reference)
.LBB0_56:
	v_pk_add_f32 v[66:67], v[66:67], v[98:99] op_sel:[0,1] op_sel_hi:[1,1] neg_lo:[0,1] neg_hi:[0,1]
	v_pk_add_f32 v[82:83], v[82:83], v[98:99] op_sel:[0,1] op_sel_hi:[1,1] neg_lo:[0,1] neg_hi:[0,1]
	v_exp_f32_e32 v66, v66
	v_exp_f32_e32 v67, v67
	v_exp_f32_e32 v82, v82
	v_exp_f32_e32 v83, v83
	v_pk_add_f32 v[68:69], v[68:69], v[98:99] op_sel:[0,1] op_sel_hi:[1,1] neg_lo:[0,1] neg_hi:[0,1]
	v_pk_add_f32 v[84:85], v[84:85], v[98:99] op_sel:[0,1] op_sel_hi:[1,1] neg_lo:[0,1] neg_hi:[0,1]
	v_exp_f32_e32 v68, v68
	v_exp_f32_e32 v69, v69
	v_exp_f32_e32 v84, v84
	v_exp_f32_e32 v85, v85
	v_pk_add_f32 v[100:101], v[66:67], v[82:83]
	v_pk_add_f32 v[70:71], v[70:71], v[98:99] op_sel:[0,1] op_sel_hi:[1,1] neg_lo:[0,1] neg_hi:[0,1]
	v_pk_add_f32 v[86:87], v[86:87], v[98:99] op_sel:[0,1] op_sel_hi:[1,1] neg_lo:[0,1] neg_hi:[0,1]
	v_exp_f32_e32 v70, v70
	v_exp_f32_e32 v71, v71
	v_exp_f32_e32 v86, v86
	v_exp_f32_e32 v87, v87
	v_pk_add_f32 v[100:101], v[100:101], v[68:69]
	v_pk_add_f32 v[100:101], v[100:101], v[84:85]
	v_pk_add_f32 v[72:73], v[72:73], v[98:99] op_sel:[0,1] op_sel_hi:[1,1] neg_lo:[0,1] neg_hi:[0,1]
	v_pk_add_f32 v[88:89], v[88:89], v[98:99] op_sel:[0,1] op_sel_hi:[1,1] neg_lo:[0,1] neg_hi:[0,1]
	v_exp_f32_e32 v72, v72
	v_exp_f32_e32 v73, v73
	v_exp_f32_e32 v88, v88
	v_exp_f32_e32 v89, v89
	v_pk_add_f32 v[100:101], v[100:101], v[70:71]
	v_pk_add_f32 v[100:101], v[100:101], v[86:87]
	v_pk_add_f32 v[74:75], v[74:75], v[98:99] op_sel:[0,1] op_sel_hi:[1,1] neg_lo:[0,1] neg_hi:[0,1]
	v_pk_add_f32 v[90:91], v[90:91], v[98:99] op_sel:[0,1] op_sel_hi:[1,1] neg_lo:[0,1] neg_hi:[0,1]
	v_exp_f32_e32 v74, v74
	v_exp_f32_e32 v75, v75
	v_exp_f32_e32 v90, v90
	v_exp_f32_e32 v91, v91
	v_pk_add_f32 v[100:101], v[100:101], v[72:73]
	v_pk_add_f32 v[100:101], v[100:101], v[88:89]
	v_pk_add_f32 v[76:77], v[76:77], v[98:99] op_sel:[0,1] op_sel_hi:[1,1] neg_lo:[0,1] neg_hi:[0,1]
	v_pk_add_f32 v[92:93], v[92:93], v[98:99] op_sel:[0,1] op_sel_hi:[1,1] neg_lo:[0,1] neg_hi:[0,1]
	v_exp_f32_e32 v76, v76
	v_exp_f32_e32 v77, v77
	v_exp_f32_e32 v92, v92
	v_exp_f32_e32 v93, v93
	v_pk_add_f32 v[100:101], v[100:101], v[74:75]
	v_pk_add_f32 v[100:101], v[100:101], v[90:91]
	v_pk_add_f32 v[78:79], v[78:79], v[98:99] op_sel:[0,1] op_sel_hi:[1,1] neg_lo:[0,1] neg_hi:[0,1]
	v_pk_add_f32 v[94:95], v[94:95], v[98:99] op_sel:[0,1] op_sel_hi:[1,1] neg_lo:[0,1] neg_hi:[0,1]
	v_exp_f32_e32 v78, v78
	v_exp_f32_e32 v79, v79
	v_exp_f32_e32 v94, v94
	v_exp_f32_e32 v95, v95
	v_pk_add_f32 v[100:101], v[100:101], v[76:77]
	v_pk_add_f32 v[100:101], v[100:101], v[92:93]
	v_pk_add_f32 v[80:81], v[80:81], v[98:99] op_sel:[0,1] op_sel_hi:[1,1] neg_lo:[0,1] neg_hi:[0,1]
	v_pk_add_f32 v[96:97], v[96:97], v[98:99] op_sel:[0,1] op_sel_hi:[1,1] neg_lo:[0,1] neg_hi:[0,1]
	v_exp_f32_e32 v80, v80
	v_exp_f32_e32 v81, v81
	v_exp_f32_e32 v96, v96
	v_exp_f32_e32 v97, v97
	v_pk_add_f32 v[100:101], v[100:101], v[78:79]
	v_pk_add_f32 v[100:101], v[100:101], v[94:95]
	s_nop 0
	v_pk_add_f32 v[100:101], v[100:101], v[80:81]
	v_pk_add_f32 v[100:101], v[100:101], v[96:97]
	v_add_f32_e32 v99, v100, v101
	s_mul_i32 s8, s48, 0x8c00
	v_fmac_f32_e32 v99, v193, v98
	v_add_u32_e32 v98, s8, v212
	v_cvt_pk_bf16_f32 v66, v66, v67
	v_cvt_pk_bf16_f32 v67, v68, v69
	v_cvt_pk_bf16_f32 v68, v70, v71
	v_cvt_pk_bf16_f32 v69, v72, v73
	v_cvt_pk_bf16_f32 v70, v74, v75
	v_cvt_pk_bf16_f32 v71, v76, v77
	v_cvt_pk_bf16_f32 v72, v78, v79
	v_cvt_pk_bf16_f32 v73, v80, v81
	v_cvt_pk_bf16_f32 v74, v82, v83
	v_cvt_pk_bf16_f32 v75, v84, v85
	v_cvt_pk_bf16_f32 v76, v86, v87
	v_cvt_pk_bf16_f32 v77, v88, v89
	v_cvt_pk_bf16_f32 v78, v90, v91
	v_cvt_pk_bf16_f32 v79, v92, v93
	v_cvt_pk_bf16_f32 v80, v94, v95
	v_cvt_pk_bf16_f32 v81, v96, v97
	ds_read_b128 v[82:85], v98 offset:17408
	ds_read_b128 v[86:89], v98 offset:22016
	ds_read_b128 v[90:93], v98 offset:26624
	ds_read_b128 v[94:97], v98 offset:31232
	s_waitcnt lgkmcnt(3)
	v_mfma_f32_32x32x16_bf16 v[50:65], v[82:85], v[66:69], v[50:65]
	s_waitcnt lgkmcnt(2)
	v_mfma_f32_32x32x16_bf16 v[34:49], v[86:89], v[66:69], v[34:49]
	s_waitcnt lgkmcnt(1)
	v_mfma_f32_32x32x16_bf16 v[18:33], v[90:93], v[66:69], v[18:33]
	s_waitcnt lgkmcnt(0)
	v_mfma_f32_32x32x16_bf16 v[2:17], v[94:97], v[66:69], v[2:17]
	ds_read_b128 v[66:69], v98 offset:17440
	ds_read_b128 v[82:85], v98 offset:22048
	ds_read_b128 v[86:89], v98 offset:26656
	ds_read_b128 v[90:93], v98 offset:31264
	s_waitcnt lgkmcnt(3)
	v_mfma_f32_32x32x16_bf16 v[50:65], v[66:69], v[70:73], v[50:65]
	s_waitcnt lgkmcnt(2)
	v_mfma_f32_32x32x16_bf16 v[34:49], v[82:85], v[70:73], v[34:49]
	s_waitcnt lgkmcnt(1)
	v_mfma_f32_32x32x16_bf16 v[18:33], v[86:89], v[70:73], v[18:33]
	s_waitcnt lgkmcnt(0)
	v_mfma_f32_32x32x16_bf16 v[2:17], v[90:93], v[70:73], v[2:17]
	ds_read_b128 v[66:69], v98 offset:17472
	ds_read_b128 v[70:73], v98 offset:22080
	ds_read_b128 v[82:85], v98 offset:26688
	ds_read_b128 v[86:89], v98 offset:31296
	s_waitcnt lgkmcnt(3)
	v_mfma_f32_32x32x16_bf16 v[50:65], v[66:69], v[74:77], v[50:65]
	s_waitcnt lgkmcnt(2)
	v_mfma_f32_32x32x16_bf16 v[34:49], v[70:73], v[74:77], v[34:49]
	s_waitcnt lgkmcnt(1)
	v_mfma_f32_32x32x16_bf16 v[18:33], v[82:85], v[74:77], v[18:33]
	s_waitcnt lgkmcnt(0)
	v_mfma_f32_32x32x16_bf16 v[2:17], v[86:89], v[74:77], v[2:17]
	ds_read_b128 v[66:69], v98 offset:17504
	ds_read_b128 v[70:73], v98 offset:22112
	ds_read_b128 v[74:77], v98 offset:26720
	ds_read_b128 v[82:85], v98 offset:31328
	s_waitcnt lgkmcnt(3)
	v_mfma_f32_32x32x16_bf16 v[50:65], v[66:69], v[78:81], v[50:65]
	s_waitcnt lgkmcnt(2)
	v_mfma_f32_32x32x16_bf16 v[34:49], v[70:73], v[78:81], v[34:49]
	s_waitcnt lgkmcnt(1)
	v_mfma_f32_32x32x16_bf16 v[18:33], v[74:77], v[78:81], v[18:33]
	s_waitcnt lgkmcnt(0)
	v_mfma_f32_32x32x16_bf16 v[2:17], v[82:85], v[78:81], v[2:17]
	v_mov_b32_e32 v193, v99

.LBB0_67:
	s_mul_i32 s0, s49, 0x8c00
	s_add_i32 s47, s0, 0
	v_add3_u32 v217, s47, v209, v210
	v_lshrrev_b32_e32 v218, v186, v202
	v_lshrrev_b32_e32 v203, v186, v203
	s_and_saveexec_b64 s[0:1], s[6:7]
	s_xor_b64 s[0:1], exec, s[0:1]
	s_cbranch_execz .LBB0_71
	v_not_b32_e32 v66, v218
	v_not_b32_e32 v82, v203
	v_bfe_i32 v83, v66, 0, 1
	v_bfe_i32 v174, v82, 0, 1
	v_bfe_i32 v67, v66, 1, 1
	v_bfe_i32 v175, v82, 1, 1
	v_bfe_i32 v68, v66, 2, 1
	v_bfe_i32 v84, v82, 2, 1
	v_bfe_i32 v69, v66, 3, 1
	v_bfe_i32 v85, v82, 3, 1
	v_bfe_i32 v70, v66, 8, 1
	v_bfe_i32 v86, v82, 8, 1
	v_bfe_i32 v71, v66, 9, 1
	v_bfe_i32 v87, v82, 9, 1
	v_bfe_i32 v72, v66, 10, 1
	v_bfe_i32 v88, v82, 10, 1
	v_bfe_i32 v73, v66, 11, 1
	v_bfe_i32 v89, v82, 11, 1
	v_bfe_i32 v74, v66, 16, 1
	v_bfe_i32 v90, v82, 16, 1
	v_bfe_i32 v75, v66, 17, 1
	v_bfe_i32 v91, v82, 17, 1
	v_bfe_i32 v76, v66, 18, 1
	v_bfe_i32 v92, v82, 18, 1
	v_bfe_i32 v77, v66, 19, 1
	v_bfe_i32 v93, v82, 19, 1
	v_bfe_i32 v78, v66, 24, 1
	v_bfe_i32 v94, v82, 24, 1
	v_bfe_i32 v79, v66, 25, 1
	v_bfe_i32 v95, v82, 25, 1
	v_bfe_i32 v80, v66, 26, 1
	v_bfe_i32 v96, v82, 26, 1
	v_bfe_i32 v66, v66, 27, 1
	v_bfe_i32 v82, v82, 27, 1
	s_nop 0
	v_and_b32_e32 v79, 0xff800000, v79
	v_and_b32_e32 v81, 0xff800000, v66
	v_and_b32_e32 v66, 0xff800000, v83
	v_and_b32_e32 v97, 0xff800000, v82
	v_and_b32_e32 v83, 0xff800000, v175
	v_and_b32_e32 v82, 0xff800000, v174
	ds_read_b128 v[218:221], v217 offset:8704
	ds_read_b128 v[222:225], v217
	ds_read_b128 v[226:229], v217 offset:32
	ds_read_b128 v[232:235], v217 offset:8736
	ds_read_b128 v[236:239], v217 offset:64
	ds_read_b128 v[248:251], v217 offset:8768
	ds_read_b128 v[240:243], v217 offset:96
	ds_read_b128 v[174:177], v217 offset:8800
	v_and_b32_e32 v80, 0xff800000, v80
	v_and_b32_e32 v78, 0xff800000, v78
	v_and_b32_e32 v77, 0xff800000, v77
	v_and_b32_e32 v76, 0xff800000, v76
	v_and_b32_e32 v75, 0xff800000, v75
	v_and_b32_e32 v74, 0xff800000, v74
	v_and_b32_e32 v73, 0xff800000, v73
	v_and_b32_e32 v72, 0xff800000, v72
	v_and_b32_e32 v71, 0xff800000, v71
	v_and_b32_e32 v70, 0xff800000, v70
	v_and_b32_e32 v69, 0xff800000, v69
	v_and_b32_e32 v68, 0xff800000, v68
	v_and_b32_e32 v67, 0xff800000, v67
	v_and_b32_e32 v96, 0xff800000, v96
	v_and_b32_e32 v95, 0xff800000, v95
	v_and_b32_e32 v94, 0xff800000, v94
	v_and_b32_e32 v93, 0xff800000, v93
	v_and_b32_e32 v92, 0xff800000, v92
	v_and_b32_e32 v91, 0xff800000, v91
	v_and_b32_e32 v90, 0xff800000, v90
	v_and_b32_e32 v89, 0xff800000, v89
	v_and_b32_e32 v88, 0xff800000, v88
	v_and_b32_e32 v87, 0xff800000, v87
	v_and_b32_e32 v86, 0xff800000, v86
	v_and_b32_e32 v85, 0xff800000, v85
	v_and_b32_e32 v84, 0xff800000, v84
	s_waitcnt lgkmcnt(6)
	v_mfma_f32_32x32x16_bf16 v[66:81], v[222:225], v[98:101], v[66:81]
	v_mfma_f32_32x32x16_bf16 v[82:97], v[218:221], v[98:101], v[82:97]
	s_waitcnt lgkmcnt(5)
	v_mfma_f32_32x32x16_bf16 v[66:81], v[226:229], v[102:105], v[66:81]
	s_waitcnt lgkmcnt(4)
	v_mfma_f32_32x32x16_bf16 v[82:97], v[232:235], v[102:105], v[82:97]
	s_waitcnt lgkmcnt(3)
	v_mfma_f32_32x32x16_bf16 v[66:81], v[236:239], v[106:109], v[66:81]
	s_waitcnt lgkmcnt(2)
	v_mfma_f32_32x32x16_bf16 v[82:97], v[248:251], v[106:109], v[82:97]
	s_waitcnt lgkmcnt(1)
	v_mfma_f32_32x32x16_bf16 v[66:81], v[240:243], v[110:113], v[66:81]
	s_waitcnt lgkmcnt(0)
	v_mfma_f32_32x32x16_bf16 v[82:97], v[174:177], v[110:113], v[82:97]
	ds_read_b128 v[174:177], v217 offset:128
	ds_read_b128 v[218:221], v217 offset:160
	ds_read_b128 v[222:225], v217 offset:8832
	ds_read_b128 v[226:229], v217 offset:8864
	ds_read_b128 v[232:235], v217 offset:192
	ds_read_b128 v[236:239], v217 offset:224
	ds_read_b128 v[240:243], v217 offset:8896
	ds_read_b128 v[248:251], v217 offset:8928
	s_waitcnt lgkmcnt(7)
	v_mfma_f32_32x32x16_bf16 v[66:81], v[174:177], v[114:117], v[66:81]
	s_waitcnt lgkmcnt(5)
	v_mfma_f32_32x32x16_bf16 v[82:97], v[222:225], v[114:117], v[82:97]
	v_mfma_f32_32x32x16_bf16 v[66:81], v[218:221], v[118:121], v[66:81]
	s_waitcnt lgkmcnt(4)
	v_mfma_f32_32x32x16_bf16 v[82:97], v[226:229], v[118:121], v[82:97]
	s_waitcnt lgkmcnt(3)
	v_mfma_f32_32x32x16_bf16 v[66:81], v[232:235], v[122:125], v[66:81]
	s_waitcnt lgkmcnt(1)
	v_mfma_f32_32x32x16_bf16 v[82:97], v[240:243], v[122:125], v[82:97]
	v_mfma_f32_32x32x16_bf16 v[66:81], v[236:239], v[126:129], v[66:81]
	s_waitcnt lgkmcnt(0)
	v_mfma_f32_32x32x16_bf16 v[82:97], v[248:251], v[126:129], v[82:97]
	v_max3_f32 v174, v231, v66, v82
	s_nop 0
	v_max3_f32 v174, v174, v67, v83
	s_nop 0
	v_max3_f32 v174, v174, v68, v84
	s_nop 0
	v_max3_f32 v174, v174, v69, v85
	s_nop 0
	v_max3_f32 v174, v174, v70, v86
	s_nop 0
	v_max3_f32 v174, v174, v71, v87
	s_nop 0
	v_max3_f32 v174, v174, v72, v88
	s_nop 0
	v_max3_f32 v174, v174, v73, v89
	s_nop 0
	v_max3_f32 v174, v174, v74, v90
	s_nop 0
	v_max3_f32 v174, v174, v75, v91
	s_nop 0
	v_max3_f32 v174, v174, v76, v92
	s_nop 0
	v_max3_f32 v174, v174, v77, v93
	s_nop 0
	v_max3_f32 v174, v174, v78, v94
	s_nop 0
	v_max3_f32 v174, v174, v79, v95
	s_nop 0
	v_max3_f32 v174, v174, v80, v96
	s_nop 0
	v_max3_f32 v174, v174, v81, v97
	s_nop 0
	v_mov_b32_e32 v175, v174
	s_nop 1
	v_permlane32_swap_b32_e32 v174, v175
	v_max_f32_e32 v174, v174, v175
	v_add_f32_e32 v175, 0x41000000, v195
	v_cmp_gt_f32_e32 vcc, v174, v175
	v_max_f32_e32 v174, v195, v174
	s_nop 0
	v_cndmask_b32_e32 v215, v195, v174, vcc
	v_cmp_neq_f32_e32 vcc, s59, v215
	s_nop 1
	v_cndmask_b32_e32 v203, 0, v215, vcc
	v_sub_f32_e32 v174, v195, v203
	v_exp_f32_e32 v202, v174
	s_nop 0
	v_cmp_eq_f32_e32 vcc, 1.0, v202
	s_cmp_eq_u64 vcc, exec
	s_cbranch_scc1 .LBB0_70
	v_pk_mul_f32 v[64:65], v[64:65], v[202:203] op_sel_hi:[1,0]
	v_pk_mul_f32 v[62:63], v[62:63], v[202:203] op_sel_hi:[1,0]
	v_pk_mul_f32 v[60:61], v[60:61], v[202:203] op_sel_hi:[1,0]
	v_pk_mul_f32 v[58:59], v[58:59], v[202:203] op_sel_hi:[1,0]
	v_pk_mul_f32 v[56:57], v[56:57], v[202:203] op_sel_hi:[1,0]
	v_pk_mul_f32 v[54:55], v[54:55], v[202:203] op_sel_hi:[1,0]
	v_pk_mul_f32 v[52:53], v[52:53], v[202:203] op_sel_hi:[1,0]
	v_pk_mul_f32 v[50:51], v[50:51], v[202:203] op_sel_hi:[1,0]
	v_pk_mul_f32 v[48:49], v[48:49], v[202:203] op_sel_hi:[1,0]
	v_pk_mul_f32 v[46:47], v[46:47], v[202:203] op_sel_hi:[1,0]
	v_pk_mul_f32 v[44:45], v[44:45], v[202:203] op_sel_hi:[1,0]
	v_pk_mul_f32 v[42:43], v[42:43], v[202:203] op_sel_hi:[1,0]
	v_pk_mul_f32 v[40:41], v[40:41], v[202:203] op_sel_hi:[1,0]
	v_pk_mul_f32 v[38:39], v[38:39], v[202:203] op_sel_hi:[1,0]
	v_pk_mul_f32 v[36:37], v[36:37], v[202:203] op_sel_hi:[1,0]
	v_pk_mul_f32 v[34:35], v[34:35], v[202:203] op_sel_hi:[1,0]
	v_pk_mul_f32 v[32:33], v[32:33], v[202:203] op_sel_hi:[1,0]
	v_pk_mul_f32 v[30:31], v[30:31], v[202:203] op_sel_hi:[1,0]
	v_pk_mul_f32 v[28:29], v[28:29], v[202:203] op_sel_hi:[1,0]
	v_pk_mul_f32 v[26:27], v[26:27], v[202:203] op_sel_hi:[1,0]
	v_pk_mul_f32 v[24:25], v[24:25], v[202:203] op_sel_hi:[1,0]
	v_pk_mul_f32 v[22:23], v[22:23], v[202:203] op_sel_hi:[1,0]
	v_pk_mul_f32 v[20:21], v[20:21], v[202:203] op_sel_hi:[1,0]
	v_pk_mul_f32 v[18:19], v[18:19], v[202:203] op_sel_hi:[1,0]
	v_pk_mul_f32 v[16:17], v[16:17], v[202:203] op_sel_hi:[1,0]
	v_pk_mul_f32 v[14:15], v[14:15], v[202:203] op_sel_hi:[1,0]
	v_pk_mul_f32 v[12:13], v[12:13], v[202:203] op_sel_hi:[1,0]
	v_pk_mul_f32 v[10:11], v[10:11], v[202:203] op_sel_hi:[1,0]
	v_pk_mul_f32 v[8:9], v[8:9], v[202:203] op_sel_hi:[1,0]
	v_pk_mul_f32 v[6:7], v[6:7], v[202:203] op_sel_hi:[1,0]
	v_pk_mul_f32 v[4:5], v[4:5], v[202:203] op_sel_hi:[1,0]
	v_pk_mul_f32 v[2:3], v[2:3], v[202:203] op_sel_hi:[1,0]
.LBB0_70:
	v_pk_add_f32 v[66:67], v[66:67], v[202:203] op_sel:[0,1] op_sel_hi:[1,1] neg_lo:[0,1] neg_hi:[0,1]
	v_pk_add_f32 v[82:83], v[82:83], v[202:203] op_sel:[0,1] op_sel_hi:[1,1] neg_lo:[0,1] neg_hi:[0,1]
	v_exp_f32_e32 v66, v66
	v_exp_f32_e32 v67, v67
	v_exp_f32_e32 v82, v82
	v_exp_f32_e32 v83, v83
	v_pk_add_f32 v[68:69], v[68:69], v[202:203] op_sel:[0,1] op_sel_hi:[1,1] neg_lo:[0,1] neg_hi:[0,1]
	v_pk_add_f32 v[84:85], v[84:85], v[202:203] op_sel:[0,1] op_sel_hi:[1,1] neg_lo:[0,1] neg_hi:[0,1]
	v_exp_f32_e32 v68, v68
	v_exp_f32_e32 v69, v69
	v_exp_f32_e32 v84, v84
	v_exp_f32_e32 v85, v85
	v_pk_add_f32 v[174:175], v[66:67], v[82:83]
	v_pk_add_f32 v[70:71], v[70:71], v[202:203] op_sel:[0,1] op_sel_hi:[1,1] neg_lo:[0,1] neg_hi:[0,1]
	v_pk_add_f32 v[86:87], v[86:87], v[202:203] op_sel:[0,1] op_sel_hi:[1,1] neg_lo:[0,1] neg_hi:[0,1]
	v_exp_f32_e32 v70, v70
	v_exp_f32_e32 v71, v71
	v_exp_f32_e32 v86, v86
	v_exp_f32_e32 v87, v87
	v_pk_add_f32 v[174:175], v[174:175], v[68:69]
	v_pk_add_f32 v[174:175], v[174:175], v[84:85]
	v_pk_add_f32 v[72:73], v[72:73], v[202:203] op_sel:[0,1] op_sel_hi:[1,1] neg_lo:[0,1] neg_hi:[0,1]
	v_pk_add_f32 v[88:89], v[88:89], v[202:203] op_sel:[0,1] op_sel_hi:[1,1] neg_lo:[0,1] neg_hi:[0,1]
	v_exp_f32_e32 v72, v72
	v_exp_f32_e32 v73, v73
	v_exp_f32_e32 v88, v88
	v_exp_f32_e32 v89, v89
	v_pk_add_f32 v[174:175], v[174:175], v[70:71]
	v_pk_add_f32 v[174:175], v[174:175], v[86:87]
	v_pk_add_f32 v[74:75], v[74:75], v[202:203] op_sel:[0,1] op_sel_hi:[1,1] neg_lo:[0,1] neg_hi:[0,1]
	v_pk_add_f32 v[90:91], v[90:91], v[202:203] op_sel:[0,1] op_sel_hi:[1,1] neg_lo:[0,1] neg_hi:[0,1]
	v_exp_f32_e32 v74, v74
	v_exp_f32_e32 v75, v75
	v_exp_f32_e32 v90, v90
	v_exp_f32_e32 v91, v91
	v_pk_add_f32 v[174:175], v[174:175], v[72:73]
	v_pk_add_f32 v[174:175], v[174:175], v[88:89]
	v_pk_add_f32 v[76:77], v[76:77], v[202:203] op_sel:[0,1] op_sel_hi:[1,1] neg_lo:[0,1] neg_hi:[0,1]
	v_pk_add_f32 v[92:93], v[92:93], v[202:203] op_sel:[0,1] op_sel_hi:[1,1] neg_lo:[0,1] neg_hi:[0,1]
	v_exp_f32_e32 v76, v76
	v_exp_f32_e32 v77, v77
	v_exp_f32_e32 v92, v92
	v_exp_f32_e32 v93, v93
	v_pk_add_f32 v[174:175], v[174:175], v[74:75]
	v_pk_add_f32 v[174:175], v[174:175], v[90:91]
	v_pk_add_f32 v[78:79], v[78:79], v[202:203] op_sel:[0,1] op_sel_hi:[1,1] neg_lo:[0,1] neg_hi:[0,1]
	v_pk_add_f32 v[94:95], v[94:95], v[202:203] op_sel:[0,1] op_sel_hi:[1,1] neg_lo:[0,1] neg_hi:[0,1]
	v_exp_f32_e32 v78, v78
	v_exp_f32_e32 v79, v79
	v_exp_f32_e32 v94, v94
	v_exp_f32_e32 v95, v95
	v_pk_add_f32 v[174:175], v[174:175], v[76:77]
	v_pk_add_f32 v[174:175], v[174:175], v[92:93]
	v_pk_add_f32 v[80:81], v[80:81], v[202:203] op_sel:[0,1] op_sel_hi:[1,1] neg_lo:[0,1] neg_hi:[0,1]
	v_pk_add_f32 v[96:97], v[96:97], v[202:203] op_sel:[0,1] op_sel_hi:[1,1] neg_lo:[0,1] neg_hi:[0,1]
	v_exp_f32_e32 v80, v80
	v_exp_f32_e32 v81, v81
	v_exp_f32_e32 v96, v96
	v_exp_f32_e32 v97, v97
	v_pk_add_f32 v[174:175], v[174:175], v[78:79]
	v_pk_add_f32 v[174:175], v[174:175], v[94:95]
	s_nop 0
	v_pk_add_f32 v[174:175], v[174:175], v[80:81]
	v_pk_add_f32 v[174:175], v[174:175], v[96:97]
	v_add_f32_e32 v216, v174, v175
	v_fmac_f32_e32 v216, v193, v202
	v_add3_u32 v193, s47, v210, v211
	v_cvt_pk_bf16_f32 v174, v66, v67
	v_cvt_pk_bf16_f32 v175, v68, v69
	v_cvt_pk_bf16_f32 v176, v70, v71
	v_cvt_pk_bf16_f32 v177, v72, v73
	v_cvt_pk_bf16_f32 v218, v74, v75
	v_cvt_pk_bf16_f32 v219, v76, v77
	v_cvt_pk_bf16_f32 v220, v78, v79
	v_cvt_pk_bf16_f32 v221, v80, v81
	v_cvt_pk_bf16_f32 v222, v82, v83
	v_cvt_pk_bf16_f32 v223, v84, v85
	v_cvt_pk_bf16_f32 v224, v86, v87
	v_cvt_pk_bf16_f32 v225, v88, v89
	v_cvt_pk_bf16_f32 v226, v90, v91
	v_cvt_pk_bf16_f32 v227, v92, v93
	v_cvt_pk_bf16_f32 v228, v94, v95
	v_cvt_pk_bf16_f32 v229, v96, v97
	ds_read_b128 v[232:235], v193 offset:17408
	ds_read_b128 v[236:239], v193 offset:22016
	ds_read_b128 v[240:243], v193 offset:26624
	ds_read_b128 v[248:251], v193 offset:31232
	s_waitcnt lgkmcnt(3)
	v_mfma_f32_32x32x16_bf16 v[50:65], v[232:235], v[174:177], v[50:65]
	s_waitcnt lgkmcnt(2)
	v_mfma_f32_32x32x16_bf16 v[34:49], v[236:239], v[174:177], v[34:49]
	s_waitcnt lgkmcnt(1)
	v_mfma_f32_32x32x16_bf16 v[18:33], v[240:243], v[174:177], v[18:33]
	s_waitcnt lgkmcnt(0)
	v_mfma_f32_32x32x16_bf16 v[2:17], v[248:251], v[174:177], v[2:17]
	ds_read_b128 v[174:177], v193 offset:17440
	ds_read_b128 v[232:235], v193 offset:22048
	ds_read_b128 v[236:239], v193 offset:26656
	ds_read_b128 v[240:243], v193 offset:31264
	s_waitcnt lgkmcnt(3)
	v_mfma_f32_32x32x16_bf16 v[50:65], v[174:177], v[218:221], v[50:65]
	s_waitcnt lgkmcnt(2)
	v_mfma_f32_32x32x16_bf16 v[34:49], v[232:235], v[218:221], v[34:49]
	s_waitcnt lgkmcnt(1)
	v_mfma_f32_32x32x16_bf16 v[18:33], v[236:239], v[218:221], v[18:33]
	s_waitcnt lgkmcnt(0)
	v_mfma_f32_32x32x16_bf16 v[2:17], v[240:243], v[218:221], v[2:17]
	ds_read_b128 v[174:177], v193 offset:17472
	ds_read_b128 v[218:221], v193 offset:22080
	ds_read_b128 v[232:235], v193 offset:26688
	ds_read_b128 v[236:239], v193 offset:31296
	s_waitcnt lgkmcnt(3)
	v_mfma_f32_32x32x16_bf16 v[50:65], v[174:177], v[222:225], v[50:65]
	s_waitcnt lgkmcnt(2)
	v_mfma_f32_32x32x16_bf16 v[34:49], v[218:221], v[222:225], v[34:49]
	s_waitcnt lgkmcnt(1)
	v_mfma_f32_32x32x16_bf16 v[18:33], v[232:235], v[222:225], v[18:33]
	s_waitcnt lgkmcnt(0)
	v_mfma_f32_32x32x16_bf16 v[2:17], v[236:239], v[222:225], v[2:17]
	ds_read_b128 v[174:177], v193 offset:17504
	ds_read_b128 v[218:221], v193 offset:22112
	ds_read_b128 v[222:225], v193 offset:26720
	ds_read_b128 v[232:235], v193 offset:31328
	s_waitcnt lgkmcnt(3)
	v_mfma_f32_32x32x16_bf16 v[50:65], v[174:177], v[226:229], v[50:65]
	s_waitcnt lgkmcnt(2)
	v_mfma_f32_32x32x16_bf16 v[34:49], v[218:221], v[226:229], v[34:49]
	s_waitcnt lgkmcnt(1)
	v_mfma_f32_32x32x16_bf16 v[18:33], v[222:225], v[226:229], v[18:33]
	s_waitcnt lgkmcnt(0)
	v_mfma_f32_32x32x16_bf16 v[2:17], v[232:235], v[226:229], v[2:17]

.LBB0_75:
	v_pk_add_f32 v[66:67], v[66:67], v[216:217] op_sel_hi:[1,0] neg_lo:[0,1] neg_hi:[0,1]
	v_pk_add_f32 v[82:83], v[82:83], v[216:217] op_sel_hi:[1,0] neg_lo:[0,1] neg_hi:[0,1]
	v_exp_f32_e32 v66, v66
	v_exp_f32_e32 v67, v67
	v_exp_f32_e32 v82, v82
	v_exp_f32_e32 v83, v83
	v_pk_add_f32 v[68:69], v[68:69], v[216:217] op_sel_hi:[1,0] neg_lo:[0,1] neg_hi:[0,1]
	v_pk_add_f32 v[84:85], v[84:85], v[216:217] op_sel_hi:[1,0] neg_lo:[0,1] neg_hi:[0,1]
	v_exp_f32_e32 v68, v68
	v_exp_f32_e32 v69, v69
	v_exp_f32_e32 v84, v84
	v_exp_f32_e32 v85, v85
	v_pk_add_f32 v[174:175], v[66:67], v[82:83]
	v_pk_add_f32 v[70:71], v[70:71], v[216:217] op_sel_hi:[1,0] neg_lo:[0,1] neg_hi:[0,1]
	v_pk_add_f32 v[86:87], v[86:87], v[216:217] op_sel_hi:[1,0] neg_lo:[0,1] neg_hi:[0,1]
	v_exp_f32_e32 v70, v70
	v_exp_f32_e32 v71, v71
	v_exp_f32_e32 v86, v86
	v_exp_f32_e32 v87, v87
	v_pk_add_f32 v[174:175], v[174:175], v[68:69]
	v_pk_add_f32 v[174:175], v[174:175], v[84:85]
	v_pk_add_f32 v[72:73], v[72:73], v[216:217] op_sel_hi:[1,0] neg_lo:[0,1] neg_hi:[0,1]
	v_pk_add_f32 v[88:89], v[88:89], v[216:217] op_sel_hi:[1,0] neg_lo:[0,1] neg_hi:[0,1]
	v_exp_f32_e32 v72, v72
	v_exp_f32_e32 v73, v73
	v_exp_f32_e32 v88, v88
	v_exp_f32_e32 v89, v89
	v_pk_add_f32 v[174:175], v[174:175], v[70:71]
	v_pk_add_f32 v[174:175], v[174:175], v[86:87]
	v_pk_add_f32 v[74:75], v[74:75], v[216:217] op_sel_hi:[1,0] neg_lo:[0,1] neg_hi:[0,1]
	v_pk_add_f32 v[90:91], v[90:91], v[216:217] op_sel_hi:[1,0] neg_lo:[0,1] neg_hi:[0,1]
	v_exp_f32_e32 v74, v74
	v_exp_f32_e32 v75, v75
	v_exp_f32_e32 v90, v90
	v_exp_f32_e32 v91, v91
	v_pk_add_f32 v[174:175], v[174:175], v[72:73]
	v_pk_add_f32 v[174:175], v[174:175], v[88:89]
	v_pk_add_f32 v[76:77], v[76:77], v[216:217] op_sel_hi:[1,0] neg_lo:[0,1] neg_hi:[0,1]
	v_pk_add_f32 v[92:93], v[92:93], v[216:217] op_sel_hi:[1,0] neg_lo:[0,1] neg_hi:[0,1]
	v_exp_f32_e32 v76, v76
	v_exp_f32_e32 v77, v77
	v_exp_f32_e32 v92, v92
	v_exp_f32_e32 v93, v93
	v_pk_add_f32 v[174:175], v[174:175], v[74:75]
	v_pk_add_f32 v[174:175], v[174:175], v[90:91]
	v_pk_add_f32 v[78:79], v[78:79], v[216:217] op_sel_hi:[1,0] neg_lo:[0,1] neg_hi:[0,1]
	v_pk_add_f32 v[94:95], v[94:95], v[216:217] op_sel_hi:[1,0] neg_lo:[0,1] neg_hi:[0,1]
	v_exp_f32_e32 v78, v78
	v_exp_f32_e32 v79, v79
	v_exp_f32_e32 v94, v94
	v_exp_f32_e32 v95, v95
	v_pk_add_f32 v[174:175], v[174:175], v[76:77]
	v_pk_add_f32 v[174:175], v[174:175], v[92:93]
	v_pk_add_f32 v[80:81], v[80:81], v[216:217] op_sel_hi:[1,0] neg_lo:[0,1] neg_hi:[0,1]
	v_pk_add_f32 v[96:97], v[96:97], v[216:217] op_sel_hi:[1,0] neg_lo:[0,1] neg_hi:[0,1]
	v_exp_f32_e32 v80, v80
	v_exp_f32_e32 v81, v81
	v_exp_f32_e32 v96, v96
	v_exp_f32_e32 v97, v97
	v_pk_add_f32 v[174:175], v[174:175], v[78:79]
	v_pk_add_f32 v[174:175], v[174:175], v[94:95]
	s_mul_i32 s48, s48, 0x8c00
	s_nop 0
	v_pk_add_f32 v[174:175], v[174:175], v[80:81]
	v_pk_add_f32 v[174:175], v[174:175], v[96:97]
	v_add_f32_e32 v216, v174, v175
	v_add_u32_e32 v174, s48, v212
	v_cvt_pk_bf16_f32 v66, v66, v67
	v_cvt_pk_bf16_f32 v67, v68, v69
	v_cvt_pk_bf16_f32 v68, v70, v71
	v_cvt_pk_bf16_f32 v69, v72, v73
	v_cvt_pk_bf16_f32 v70, v74, v75
	v_cvt_pk_bf16_f32 v71, v76, v77
	v_cvt_pk_bf16_f32 v72, v78, v79
	v_cvt_pk_bf16_f32 v73, v80, v81
	v_cvt_pk_bf16_f32 v74, v82, v83
	v_cvt_pk_bf16_f32 v75, v84, v85
	v_cvt_pk_bf16_f32 v76, v86, v87
	v_cvt_pk_bf16_f32 v77, v88, v89
	v_cvt_pk_bf16_f32 v78, v90, v91
	v_cvt_pk_bf16_f32 v79, v92, v93
	v_cvt_pk_bf16_f32 v80, v94, v95
	v_cvt_pk_bf16_f32 v81, v96, v97
	ds_read_b128 v[82:85], v174 offset:17408
	ds_read_b128 v[86:89], v174 offset:22016
	ds_read_b128 v[90:93], v174 offset:26624
	ds_read_b128 v[94:97], v174 offset:31232
	v_fmac_f32_e32 v216, v193, v202
	s_waitcnt lgkmcnt(3)
	v_mfma_f32_32x32x16_bf16 v[50:65], v[82:85], v[66:69], v[50:65]
	s_waitcnt lgkmcnt(2)
	v_mfma_f32_32x32x16_bf16 v[34:49], v[86:89], v[66:69], v[34:49]
	s_waitcnt lgkmcnt(1)
	v_mfma_f32_32x32x16_bf16 v[18:33], v[90:93], v[66:69], v[18:33]
	s_waitcnt lgkmcnt(0)
	v_mfma_f32_32x32x16_bf16 v[2:17], v[94:97], v[66:69], v[2:17]
	ds_read_b128 v[66:69], v174 offset:17440
	ds_read_b128 v[82:85], v174 offset:22048
	ds_read_b128 v[86:89], v174 offset:26656
	ds_read_b128 v[90:93], v174 offset:31264
	s_waitcnt lgkmcnt(3)
	v_mfma_f32_32x32x16_bf16 v[50:65], v[66:69], v[70:73], v[50:65]
	s_waitcnt lgkmcnt(2)
	v_mfma_f32_32x32x16_bf16 v[34:49], v[82:85], v[70:73], v[34:49]
	s_waitcnt lgkmcnt(1)
	v_mfma_f32_32x32x16_bf16 v[18:33], v[86:89], v[70:73], v[18:33]
	s_waitcnt lgkmcnt(0)
	v_mfma_f32_32x32x16_bf16 v[2:17], v[90:93], v[70:73], v[2:17]
	ds_read_b128 v[66:69], v174 offset:17472
	ds_read_b128 v[70:73], v174 offset:22080
	ds_read_b128 v[82:85], v174 offset:26688
	ds_read_b128 v[86:89], v174 offset:31296
	s_waitcnt lgkmcnt(3)
	v_mfma_f32_32x32x16_bf16 v[50:65], v[66:69], v[74:77], v[50:65]
	s_waitcnt lgkmcnt(2)
	v_mfma_f32_32x32x16_bf16 v[34:49], v[70:73], v[74:77], v[34:49]
	s_waitcnt lgkmcnt(1)
	v_mfma_f32_32x32x16_bf16 v[18:33], v[82:85], v[74:77], v[18:33]
	s_waitcnt lgkmcnt(0)
	v_mfma_f32_32x32x16_bf16 v[2:17], v[86:89], v[74:77], v[2:17]
	ds_read_b128 v[66:69], v174 offset:17504
	ds_read_b128 v[70:73], v174 offset:22112
	ds_read_b128 v[74:77], v174 offset:26720
	ds_read_b128 v[82:85], v174 offset:31328
	s_waitcnt lgkmcnt(3)
	v_mfma_f32_32x32x16_bf16 v[50:65], v[66:69], v[78:81], v[50:65]
	s_waitcnt lgkmcnt(2)
	v_mfma_f32_32x32x16_bf16 v[34:49], v[70:73], v[78:81], v[34:49]
	s_waitcnt lgkmcnt(1)
	v_mfma_f32_32x32x16_bf16 v[18:33], v[74:77], v[78:81], v[18:33]
	s_waitcnt lgkmcnt(0)
	v_mfma_f32_32x32x16_bf16 v[2:17], v[82:85], v[78:81], v[2:17]
	s_branch .LBB0_77

.LBB0_77:
	v_not_b32_e32 v66, v218
	v_not_b32_e32 v82, v203
	v_bfe_i32 v83, v66, 0, 1
	v_bfe_i32 v174, v82, 0, 1
	v_bfe_i32 v67, v66, 1, 1
	v_bfe_i32 v175, v82, 1, 1
	v_bfe_i32 v68, v66, 2, 1
	v_bfe_i32 v84, v82, 2, 1
	v_bfe_i32 v69, v66, 3, 1
	v_bfe_i32 v85, v82, 3, 1
	v_bfe_i32 v70, v66, 8, 1
	v_bfe_i32 v86, v82, 8, 1
	v_bfe_i32 v71, v66, 9, 1
	v_bfe_i32 v87, v82, 9, 1
	v_bfe_i32 v72, v66, 10, 1
	v_bfe_i32 v88, v82, 10, 1
	v_bfe_i32 v73, v66, 11, 1
	v_bfe_i32 v89, v82, 11, 1
	v_bfe_i32 v74, v66, 16, 1
	v_bfe_i32 v90, v82, 16, 1
	v_bfe_i32 v75, v66, 17, 1
	v_bfe_i32 v91, v82, 17, 1
	v_bfe_i32 v76, v66, 18, 1
	v_bfe_i32 v92, v82, 18, 1
	v_bfe_i32 v77, v66, 19, 1
	v_bfe_i32 v93, v82, 19, 1
	v_bfe_i32 v78, v66, 24, 1
	v_bfe_i32 v94, v82, 24, 1
	v_bfe_i32 v79, v66, 25, 1
	v_bfe_i32 v95, v82, 25, 1
	v_bfe_i32 v80, v66, 26, 1
	v_bfe_i32 v96, v82, 26, 1
	v_bfe_i32 v66, v66, 27, 1
	v_bfe_i32 v82, v82, 27, 1
	s_nop 0
	v_and_b32_e32 v79, 0xff800000, v79
	v_and_b32_e32 v81, 0xff800000, v66
	v_and_b32_e32 v66, 0xff800000, v83
	v_and_b32_e32 v97, 0xff800000, v82
	v_and_b32_e32 v83, 0xff800000, v175
	v_and_b32_e32 v82, 0xff800000, v174
	ds_read_b128 v[174:177], v217 offset:8704
	ds_read_b128 v[218:221], v217
	ds_read_b128 v[222:225], v217 offset:32
	ds_read_b128 v[226:229], v217 offset:8736
	ds_read_b128 v[232:235], v217 offset:64
	ds_read_b128 v[236:239], v217 offset:8768
	ds_read_b128 v[240:243], v217 offset:96
	ds_read_b128 v[248:251], v217 offset:8800
	v_and_b32_e32 v80, 0xff800000, v80
	v_and_b32_e32 v78, 0xff800000, v78
	v_and_b32_e32 v77, 0xff800000, v77
	v_and_b32_e32 v76, 0xff800000, v76
	v_and_b32_e32 v75, 0xff800000, v75
	v_and_b32_e32 v74, 0xff800000, v74
	v_and_b32_e32 v73, 0xff800000, v73
	v_and_b32_e32 v72, 0xff800000, v72
	v_and_b32_e32 v71, 0xff800000, v71
	v_and_b32_e32 v70, 0xff800000, v70
	v_and_b32_e32 v69, 0xff800000, v69
	v_and_b32_e32 v68, 0xff800000, v68
	v_and_b32_e32 v67, 0xff800000, v67
	v_and_b32_e32 v96, 0xff800000, v96
	v_and_b32_e32 v95, 0xff800000, v95
	v_and_b32_e32 v94, 0xff800000, v94
	v_and_b32_e32 v93, 0xff800000, v93
	v_and_b32_e32 v92, 0xff800000, v92
	v_and_b32_e32 v91, 0xff800000, v91
	v_and_b32_e32 v90, 0xff800000, v90
	v_and_b32_e32 v89, 0xff800000, v89
	v_and_b32_e32 v88, 0xff800000, v88
	v_and_b32_e32 v87, 0xff800000, v87
	v_and_b32_e32 v86, 0xff800000, v86
	v_and_b32_e32 v85, 0xff800000, v85
	v_and_b32_e32 v84, 0xff800000, v84
	s_waitcnt lgkmcnt(6)
	v_mfma_f32_32x32x16_bf16 v[66:81], v[218:221], v[98:101], v[66:81]
	v_mfma_f32_32x32x16_bf16 v[82:97], v[174:177], v[98:101], v[82:97]
	s_waitcnt lgkmcnt(5)
	v_mfma_f32_32x32x16_bf16 v[66:81], v[222:225], v[102:105], v[66:81]
	s_waitcnt lgkmcnt(4)
	v_mfma_f32_32x32x16_bf16 v[82:97], v[226:229], v[102:105], v[82:97]
	s_waitcnt lgkmcnt(3)
	v_mfma_f32_32x32x16_bf16 v[66:81], v[232:235], v[106:109], v[66:81]
	s_waitcnt lgkmcnt(2)
	v_mfma_f32_32x32x16_bf16 v[82:97], v[236:239], v[106:109], v[82:97]
	s_waitcnt lgkmcnt(1)
	v_mfma_f32_32x32x16_bf16 v[66:81], v[240:243], v[110:113], v[66:81]
	s_waitcnt lgkmcnt(0)
	v_mfma_f32_32x32x16_bf16 v[82:97], v[248:251], v[110:113], v[82:97]
	ds_read_b128 v[174:177], v217 offset:128
	ds_read_b128 v[218:221], v217 offset:160
	ds_read_b128 v[222:225], v217 offset:8832
	ds_read_b128 v[226:229], v217 offset:8864
	ds_read_b128 v[232:235], v217 offset:192
	ds_read_b128 v[236:239], v217 offset:224
	ds_read_b128 v[240:243], v217 offset:8896
	ds_read_b128 v[248:251], v217 offset:8928
	s_waitcnt lgkmcnt(7)
	v_mfma_f32_32x32x16_bf16 v[66:81], v[174:177], v[114:117], v[66:81]
	s_waitcnt lgkmcnt(5)
	v_mfma_f32_32x32x16_bf16 v[82:97], v[222:225], v[114:117], v[82:97]
	v_mfma_f32_32x32x16_bf16 v[66:81], v[218:221], v[118:121], v[66:81]
	s_waitcnt lgkmcnt(4)
	v_mfma_f32_32x32x16_bf16 v[82:97], v[226:229], v[118:121], v[82:97]
	s_waitcnt lgkmcnt(3)
	v_mfma_f32_32x32x16_bf16 v[66:81], v[232:235], v[122:125], v[66:81]
	s_waitcnt lgkmcnt(1)
	v_mfma_f32_32x32x16_bf16 v[82:97], v[240:243], v[122:125], v[82:97]
	v_mfma_f32_32x32x16_bf16 v[66:81], v[236:239], v[126:129], v[66:81]
	s_waitcnt lgkmcnt(0)
	v_mfma_f32_32x32x16_bf16 v[82:97], v[248:251], v[126:129], v[82:97]

.LBB0_90:
	v_not_b32_e32 v66, v218
	v_not_b32_e32 v82, v205
	v_bfe_i32 v83, v66, 0, 1
	v_bfe_i32 v174, v82, 0, 1
	v_bfe_i32 v67, v66, 1, 1
	v_bfe_i32 v175, v82, 1, 1
	v_bfe_i32 v68, v66, 2, 1
	v_bfe_i32 v84, v82, 2, 1
	v_bfe_i32 v69, v66, 3, 1
	v_bfe_i32 v85, v82, 3, 1
	v_bfe_i32 v70, v66, 8, 1
	v_bfe_i32 v86, v82, 8, 1
	v_bfe_i32 v71, v66, 9, 1
	v_bfe_i32 v87, v82, 9, 1
	v_bfe_i32 v72, v66, 10, 1
	v_bfe_i32 v88, v82, 10, 1
	v_bfe_i32 v73, v66, 11, 1
	v_bfe_i32 v89, v82, 11, 1
	v_bfe_i32 v74, v66, 16, 1
	v_bfe_i32 v90, v82, 16, 1
	v_bfe_i32 v75, v66, 17, 1
	v_bfe_i32 v91, v82, 17, 1
	v_bfe_i32 v76, v66, 18, 1
	v_bfe_i32 v92, v82, 18, 1
	v_bfe_i32 v77, v66, 19, 1
	v_bfe_i32 v93, v82, 19, 1
	v_bfe_i32 v78, v66, 24, 1
	v_bfe_i32 v94, v82, 24, 1
	v_bfe_i32 v79, v66, 25, 1
	v_bfe_i32 v95, v82, 25, 1
	v_bfe_i32 v80, v66, 26, 1
	v_bfe_i32 v96, v82, 26, 1
	v_bfe_i32 v66, v66, 27, 1
	v_bfe_i32 v82, v82, 27, 1
	s_nop 0
	v_and_b32_e32 v79, 0xff800000, v79
	v_and_b32_e32 v81, 0xff800000, v66
	v_and_b32_e32 v66, 0xff800000, v83
	v_and_b32_e32 v97, 0xff800000, v82
	v_and_b32_e32 v83, 0xff800000, v175
	v_and_b32_e32 v82, 0xff800000, v174
	ds_read_b128 v[174:177], v217 offset:8704
	ds_read_b128 v[218:221], v217
	ds_read_b128 v[222:225], v217 offset:32
	ds_read_b128 v[226:229], v217 offset:8736
	ds_read_b128 v[232:235], v217 offset:64
	ds_read_b128 v[236:239], v217 offset:8768
	ds_read_b128 v[240:243], v217 offset:96
	ds_read_b128 v[248:251], v217 offset:8800
	v_and_b32_e32 v80, 0xff800000, v80
	v_and_b32_e32 v78, 0xff800000, v78
	v_and_b32_e32 v77, 0xff800000, v77
	v_and_b32_e32 v76, 0xff800000, v76
	v_and_b32_e32 v75, 0xff800000, v75
	v_and_b32_e32 v74, 0xff800000, v74
	v_and_b32_e32 v73, 0xff800000, v73
	v_and_b32_e32 v72, 0xff800000, v72
	v_and_b32_e32 v71, 0xff800000, v71
	v_and_b32_e32 v70, 0xff800000, v70
	v_and_b32_e32 v69, 0xff800000, v69
	v_and_b32_e32 v68, 0xff800000, v68
	v_and_b32_e32 v67, 0xff800000, v67
	v_and_b32_e32 v96, 0xff800000, v96
	v_and_b32_e32 v95, 0xff800000, v95
	v_and_b32_e32 v94, 0xff800000, v94
	v_and_b32_e32 v93, 0xff800000, v93
	v_and_b32_e32 v92, 0xff800000, v92
	v_and_b32_e32 v91, 0xff800000, v91
	v_and_b32_e32 v90, 0xff800000, v90
	v_and_b32_e32 v89, 0xff800000, v89
	v_and_b32_e32 v88, 0xff800000, v88
	v_and_b32_e32 v87, 0xff800000, v87
	v_and_b32_e32 v86, 0xff800000, v86
	v_and_b32_e32 v85, 0xff800000, v85
	v_and_b32_e32 v84, 0xff800000, v84
	s_waitcnt lgkmcnt(6)
	v_mfma_f32_32x32x16_bf16 v[66:81], v[218:221], v[98:101], v[66:81]
	v_mfma_f32_32x32x16_bf16 v[82:97], v[174:177], v[98:101], v[82:97]
	s_waitcnt lgkmcnt(5)
	v_mfma_f32_32x32x16_bf16 v[66:81], v[222:225], v[102:105], v[66:81]
	s_waitcnt lgkmcnt(4)
	v_mfma_f32_32x32x16_bf16 v[82:97], v[226:229], v[102:105], v[82:97]
	s_waitcnt lgkmcnt(3)
	v_mfma_f32_32x32x16_bf16 v[66:81], v[232:235], v[106:109], v[66:81]
	s_waitcnt lgkmcnt(2)
	v_mfma_f32_32x32x16_bf16 v[82:97], v[236:239], v[106:109], v[82:97]
	s_waitcnt lgkmcnt(1)
	v_mfma_f32_32x32x16_bf16 v[66:81], v[240:243], v[110:113], v[66:81]
	s_waitcnt lgkmcnt(0)
	v_mfma_f32_32x32x16_bf16 v[82:97], v[248:251], v[110:113], v[82:97]
	ds_read_b128 v[174:177], v217 offset:128
	ds_read_b128 v[218:221], v217 offset:160
	ds_read_b128 v[222:225], v217 offset:8832
	ds_read_b128 v[226:229], v217 offset:8864
	ds_read_b128 v[232:235], v217 offset:192
	ds_read_b128 v[236:239], v217 offset:224
	ds_read_b128 v[240:243], v217 offset:8896
	ds_read_b128 v[248:251], v217 offset:8928
	s_waitcnt lgkmcnt(7)
	v_mfma_f32_32x32x16_bf16 v[66:81], v[174:177], v[114:117], v[66:81]
	s_waitcnt lgkmcnt(5)
	v_mfma_f32_32x32x16_bf16 v[82:97], v[222:225], v[114:117], v[82:97]
	v_mfma_f32_32x32x16_bf16 v[66:81], v[218:221], v[118:121], v[66:81]
	s_waitcnt lgkmcnt(4)
	v_mfma_f32_32x32x16_bf16 v[82:97], v[226:229], v[118:121], v[82:97]
	s_waitcnt lgkmcnt(3)
	v_mfma_f32_32x32x16_bf16 v[66:81], v[232:235], v[122:125], v[66:81]
	s_waitcnt lgkmcnt(1)
	v_mfma_f32_32x32x16_bf16 v[82:97], v[240:243], v[122:125], v[82:97]
	v_mfma_f32_32x32x16_bf16 v[66:81], v[236:239], v[126:129], v[66:81]
	s_waitcnt lgkmcnt(0)
	v_mfma_f32_32x32x16_bf16 v[82:97], v[248:251], v[126:129], v[82:97]
	v_max3_f32 v174, v231, v66, v82
	s_nop 0
	v_max3_f32 v174, v174, v67, v83
	s_nop 0
	v_max3_f32 v174, v174, v68, v84
	s_nop 0
	v_max3_f32 v174, v174, v69, v85
	s_nop 0
	v_max3_f32 v174, v174, v70, v86
	s_nop 0
	v_max3_f32 v174, v174, v71, v87
	s_nop 0
	v_max3_f32 v174, v174, v72, v88
	s_nop 0
	v_max3_f32 v174, v174, v73, v89
	s_nop 0
	v_max3_f32 v174, v174, v74, v90
	s_nop 0
	v_max3_f32 v174, v174, v75, v91
	s_nop 0
	v_max3_f32 v174, v174, v76, v92
	s_nop 0
	v_max3_f32 v174, v174, v77, v93
	s_nop 0
	v_max3_f32 v174, v174, v78, v94
	s_nop 0
	v_max3_f32 v174, v174, v79, v95
	s_nop 0
	v_max3_f32 v174, v174, v80, v96
	s_nop 0
	v_max3_f32 v174, v174, v81, v97
	s_nop 0
	v_mov_b32_e32 v175, v174
	s_nop 1
	v_permlane32_swap_b32_e32 v174, v175
	v_max_f32_e32 v174, v174, v175
	v_add_f32_e32 v175, 0x41000000, v215
	v_cmp_gt_f32_e32 vcc, v174, v175
	v_max_f32_e32 v174, v215, v174
	s_nop 0
	v_cndmask_b32_e32 v195, v215, v174, vcc
	v_cmp_neq_f32_e32 vcc, s59, v195
	s_nop 1
	v_cndmask_b32_e32 v193, 0, v195, vcc
	v_sub_f32_e32 v174, v215, v193
	v_exp_f32_e32 v204, v174
	s_nop 0
	v_cmp_eq_f32_e32 vcc, 1.0, v204
	s_cmp_eq_u64 vcc, exec
	s_cbranch_scc1 .LBB0_92
	v_pk_mul_f32 v[64:65], v[64:65], v[204:205] op_sel_hi:[1,0]
	v_pk_mul_f32 v[62:63], v[62:63], v[204:205] op_sel_hi:[1,0]
	v_pk_mul_f32 v[60:61], v[60:61], v[204:205] op_sel_hi:[1,0]
	v_pk_mul_f32 v[58:59], v[58:59], v[204:205] op_sel_hi:[1,0]
	v_pk_mul_f32 v[56:57], v[56:57], v[204:205] op_sel_hi:[1,0]
	v_pk_mul_f32 v[54:55], v[54:55], v[204:205] op_sel_hi:[1,0]
	v_pk_mul_f32 v[52:53], v[52:53], v[204:205] op_sel_hi:[1,0]
	v_pk_mul_f32 v[50:51], v[50:51], v[204:205] op_sel_hi:[1,0]
	v_pk_mul_f32 v[48:49], v[48:49], v[204:205] op_sel_hi:[1,0]
	v_pk_mul_f32 v[46:47], v[46:47], v[204:205] op_sel_hi:[1,0]
	v_pk_mul_f32 v[44:45], v[44:45], v[204:205] op_sel_hi:[1,0]
	v_pk_mul_f32 v[42:43], v[42:43], v[204:205] op_sel_hi:[1,0]
	v_pk_mul_f32 v[40:41], v[40:41], v[204:205] op_sel_hi:[1,0]
	v_pk_mul_f32 v[38:39], v[38:39], v[204:205] op_sel_hi:[1,0]
	v_pk_mul_f32 v[36:37], v[36:37], v[204:205] op_sel_hi:[1,0]
	v_pk_mul_f32 v[34:35], v[34:35], v[204:205] op_sel_hi:[1,0]
	v_pk_mul_f32 v[32:33], v[32:33], v[204:205] op_sel_hi:[1,0]
	v_pk_mul_f32 v[30:31], v[30:31], v[204:205] op_sel_hi:[1,0]
	v_pk_mul_f32 v[28:29], v[28:29], v[204:205] op_sel_hi:[1,0]
	v_pk_mul_f32 v[26:27], v[26:27], v[204:205] op_sel_hi:[1,0]
	v_pk_mul_f32 v[24:25], v[24:25], v[204:205] op_sel_hi:[1,0]
	v_pk_mul_f32 v[22:23], v[22:23], v[204:205] op_sel_hi:[1,0]
	v_pk_mul_f32 v[20:21], v[20:21], v[204:205] op_sel_hi:[1,0]
	v_pk_mul_f32 v[18:19], v[18:19], v[204:205] op_sel_hi:[1,0]
	v_pk_mul_f32 v[16:17], v[16:17], v[204:205] op_sel_hi:[1,0]
	v_pk_mul_f32 v[14:15], v[14:15], v[204:205] op_sel_hi:[1,0]
	v_pk_mul_f32 v[12:13], v[12:13], v[204:205] op_sel_hi:[1,0]
	v_pk_mul_f32 v[10:11], v[10:11], v[204:205] op_sel_hi:[1,0]
	v_pk_mul_f32 v[8:9], v[8:9], v[204:205] op_sel_hi:[1,0]
	v_pk_mul_f32 v[6:7], v[6:7], v[204:205] op_sel_hi:[1,0]
	v_pk_mul_f32 v[4:5], v[4:5], v[204:205] op_sel_hi:[1,0]
	v_pk_mul_f32 v[2:3], v[2:3], v[204:205] op_sel_hi:[1,0]
.LBB0_92:
	v_pk_add_f32 v[66:67], v[66:67], v[192:193] op_sel:[0,1] op_sel_hi:[1,1] neg_lo:[0,1] neg_hi:[0,1]
	v_pk_add_f32 v[82:83], v[82:83], v[192:193] op_sel:[0,1] op_sel_hi:[1,1] neg_lo:[0,1] neg_hi:[0,1]
	v_exp_f32_e32 v66, v66
	v_exp_f32_e32 v67, v67
	v_exp_f32_e32 v82, v82
	v_exp_f32_e32 v83, v83
	v_pk_add_f32 v[68:69], v[68:69], v[192:193] op_sel:[0,1] op_sel_hi:[1,1] neg_lo:[0,1] neg_hi:[0,1]
	v_pk_add_f32 v[84:85], v[84:85], v[192:193] op_sel:[0,1] op_sel_hi:[1,1] neg_lo:[0,1] neg_hi:[0,1]
	v_exp_f32_e32 v68, v68
	v_exp_f32_e32 v69, v69
	v_exp_f32_e32 v84, v84
	v_exp_f32_e32 v85, v85
	v_pk_add_f32 v[174:175], v[66:67], v[82:83]
	v_pk_add_f32 v[70:71], v[70:71], v[192:193] op_sel:[0,1] op_sel_hi:[1,1] neg_lo:[0,1] neg_hi:[0,1]
	v_pk_add_f32 v[86:87], v[86:87], v[192:193] op_sel:[0,1] op_sel_hi:[1,1] neg_lo:[0,1] neg_hi:[0,1]
	v_exp_f32_e32 v70, v70
	v_exp_f32_e32 v71, v71
	v_exp_f32_e32 v86, v86
	v_exp_f32_e32 v87, v87
	v_pk_add_f32 v[174:175], v[174:175], v[68:69]
	v_pk_add_f32 v[174:175], v[174:175], v[84:85]
	v_pk_add_f32 v[72:73], v[72:73], v[192:193] op_sel:[0,1] op_sel_hi:[1,1] neg_lo:[0,1] neg_hi:[0,1]
	v_pk_add_f32 v[88:89], v[88:89], v[192:193] op_sel:[0,1] op_sel_hi:[1,1] neg_lo:[0,1] neg_hi:[0,1]
	v_exp_f32_e32 v72, v72
	v_exp_f32_e32 v73, v73
	v_exp_f32_e32 v88, v88
	v_exp_f32_e32 v89, v89
	v_pk_add_f32 v[174:175], v[174:175], v[70:71]
	v_pk_add_f32 v[174:175], v[174:175], v[86:87]
	v_pk_add_f32 v[74:75], v[74:75], v[192:193] op_sel:[0,1] op_sel_hi:[1,1] neg_lo:[0,1] neg_hi:[0,1]
	v_pk_add_f32 v[90:91], v[90:91], v[192:193] op_sel:[0,1] op_sel_hi:[1,1] neg_lo:[0,1] neg_hi:[0,1]
	v_exp_f32_e32 v74, v74
	v_exp_f32_e32 v75, v75
	v_exp_f32_e32 v90, v90
	v_exp_f32_e32 v91, v91
	v_pk_add_f32 v[174:175], v[174:175], v[72:73]
	v_pk_add_f32 v[174:175], v[174:175], v[88:89]
	v_pk_add_f32 v[76:77], v[76:77], v[192:193] op_sel:[0,1] op_sel_hi:[1,1] neg_lo:[0,1] neg_hi:[0,1]
	v_pk_add_f32 v[92:93], v[92:93], v[192:193] op_sel:[0,1] op_sel_hi:[1,1] neg_lo:[0,1] neg_hi:[0,1]
	v_exp_f32_e32 v76, v76
	v_exp_f32_e32 v77, v77
	v_exp_f32_e32 v92, v92
	v_exp_f32_e32 v93, v93
	v_pk_add_f32 v[174:175], v[174:175], v[74:75]
	v_pk_add_f32 v[174:175], v[174:175], v[90:91]
	v_pk_add_f32 v[78:79], v[78:79], v[192:193] op_sel:[0,1] op_sel_hi:[1,1] neg_lo:[0,1] neg_hi:[0,1]
	v_pk_add_f32 v[94:95], v[94:95], v[192:193] op_sel:[0,1] op_sel_hi:[1,1] neg_lo:[0,1] neg_hi:[0,1]
	v_exp_f32_e32 v78, v78
	v_exp_f32_e32 v79, v79
	v_exp_f32_e32 v94, v94
	v_exp_f32_e32 v95, v95
	v_pk_add_f32 v[174:175], v[174:175], v[76:77]
	v_pk_add_f32 v[174:175], v[174:175], v[92:93]
	v_pk_add_f32 v[80:81], v[80:81], v[192:193] op_sel:[0,1] op_sel_hi:[1,1] neg_lo:[0,1] neg_hi:[0,1]
	v_pk_add_f32 v[96:97], v[96:97], v[192:193] op_sel:[0,1] op_sel_hi:[1,1] neg_lo:[0,1] neg_hi:[0,1]
	v_exp_f32_e32 v80, v80
	v_exp_f32_e32 v81, v81
	v_exp_f32_e32 v96, v96
	v_exp_f32_e32 v97, v97
	v_pk_add_f32 v[174:175], v[174:175], v[78:79]
	v_pk_add_f32 v[174:175], v[174:175], v[94:95]
	s_nop 0
	v_pk_add_f32 v[174:175], v[174:175], v[80:81]
	v_pk_add_f32 v[174:175], v[174:175], v[96:97]
	v_add_f32_e32 v193, v174, v175
	v_fmac_f32_e32 v193, v216, v204
	v_add3_u32 v204, s30, v210, v211
	v_cvt_pk_bf16_f32 v174, v66, v67
	v_cvt_pk_bf16_f32 v175, v68, v69
	v_cvt_pk_bf16_f32 v176, v70, v71
	v_cvt_pk_bf16_f32 v177, v72, v73
	v_cvt_pk_bf16_f32 v216, v74, v75
	v_cvt_pk_bf16_f32 v217, v76, v77
	v_cvt_pk_bf16_f32 v218, v78, v79
	v_cvt_pk_bf16_f32 v219, v80, v81
	v_cvt_pk_bf16_f32 v220, v82, v83
	v_cvt_pk_bf16_f32 v221, v84, v85
	v_cvt_pk_bf16_f32 v222, v86, v87
	v_cvt_pk_bf16_f32 v223, v88, v89
	v_cvt_pk_bf16_f32 v224, v90, v91
	v_cvt_pk_bf16_f32 v225, v92, v93
	v_cvt_pk_bf16_f32 v226, v94, v95
	v_cvt_pk_bf16_f32 v227, v96, v97
	ds_read_b128 v[232:235], v204 offset:17408
	ds_read_b128 v[236:239], v204 offset:22016
	ds_read_b128 v[240:243], v204 offset:26624
	ds_read_b128 v[248:251], v204 offset:31232
	s_waitcnt lgkmcnt(3)
	v_mfma_f32_32x32x16_bf16 v[50:65], v[232:235], v[174:177], v[50:65]
	s_waitcnt lgkmcnt(2)
	v_mfma_f32_32x32x16_bf16 v[34:49], v[236:239], v[174:177], v[34:49]
	s_waitcnt lgkmcnt(1)
	v_mfma_f32_32x32x16_bf16 v[18:33], v[240:243], v[174:177], v[18:33]
	s_waitcnt lgkmcnt(0)
	v_mfma_f32_32x32x16_bf16 v[2:17], v[248:251], v[174:177], v[2:17]
	ds_read_b128 v[174:177], v204 offset:17440
	ds_read_b128 v[232:235], v204 offset:22048
	ds_read_b128 v[236:239], v204 offset:26656
	ds_read_b128 v[240:243], v204 offset:31264
	s_waitcnt lgkmcnt(3)
	v_mfma_f32_32x32x16_bf16 v[50:65], v[174:177], v[216:219], v[50:65]
	s_waitcnt lgkmcnt(2)
	v_mfma_f32_32x32x16_bf16 v[34:49], v[232:235], v[216:219], v[34:49]
	s_waitcnt lgkmcnt(1)
	v_mfma_f32_32x32x16_bf16 v[18:33], v[236:239], v[216:219], v[18:33]
	s_waitcnt lgkmcnt(0)
	v_mfma_f32_32x32x16_bf16 v[2:17], v[240:243], v[216:219], v[2:17]
	ds_read_b128 v[174:177], v204 offset:17472
	ds_read_b128 v[216:219], v204 offset:22080
	ds_read_b128 v[232:235], v204 offset:26688
	ds_read_b128 v[236:239], v204 offset:31296
	s_waitcnt lgkmcnt(3)
	v_mfma_f32_32x32x16_bf16 v[50:65], v[174:177], v[220:223], v[50:65]
	s_waitcnt lgkmcnt(2)
	v_mfma_f32_32x32x16_bf16 v[34:49], v[216:219], v[220:223], v[34:49]
	s_waitcnt lgkmcnt(1)
	v_mfma_f32_32x32x16_bf16 v[18:33], v[232:235], v[220:223], v[18:33]
	s_waitcnt lgkmcnt(0)
	v_mfma_f32_32x32x16_bf16 v[2:17], v[236:239], v[220:223], v[2:17]
	ds_read_b128 v[174:177], v204 offset:17504
	ds_read_b128 v[216:219], v204 offset:22112
	ds_read_b128 v[220:223], v204 offset:26720
	ds_read_b128 v[232:235], v204 offset:31328
	s_waitcnt lgkmcnt(3)
	v_mfma_f32_32x32x16_bf16 v[50:65], v[174:177], v[224:227], v[50:65]
	s_waitcnt lgkmcnt(2)
	v_mfma_f32_32x32x16_bf16 v[34:49], v[216:219], v[224:227], v[34:49]
	s_waitcnt lgkmcnt(1)
	v_mfma_f32_32x32x16_bf16 v[18:33], v[220:223], v[224:227], v[18:33]
	s_waitcnt lgkmcnt(0)
	v_mfma_f32_32x32x16_bf16 v[2:17], v[232:235], v[224:227], v[2:17]
	s_andn2_saveexec_b64 s[0:1], s[0:1]
	s_cbranch_execz .LBB0_87

.LBB0_95:
	v_pk_add_f32 v[66:67], v[66:67], v[192:193] op_sel:[0,1] op_sel_hi:[1,1] neg_lo:[0,1] neg_hi:[0,1]
	v_pk_add_f32 v[82:83], v[82:83], v[192:193] op_sel:[0,1] op_sel_hi:[1,1] neg_lo:[0,1] neg_hi:[0,1]
	v_exp_f32_e32 v66, v66
	v_exp_f32_e32 v67, v67
	v_exp_f32_e32 v82, v82
	v_exp_f32_e32 v83, v83
	v_pk_add_f32 v[68:69], v[68:69], v[192:193] op_sel:[0,1] op_sel_hi:[1,1] neg_lo:[0,1] neg_hi:[0,1]
	v_pk_add_f32 v[84:85], v[84:85], v[192:193] op_sel:[0,1] op_sel_hi:[1,1] neg_lo:[0,1] neg_hi:[0,1]
	v_exp_f32_e32 v68, v68
	v_exp_f32_e32 v69, v69
	v_exp_f32_e32 v84, v84
	v_exp_f32_e32 v85, v85
	v_pk_add_f32 v[174:175], v[66:67], v[82:83]
	v_pk_add_f32 v[70:71], v[70:71], v[192:193] op_sel:[0,1] op_sel_hi:[1,1] neg_lo:[0,1] neg_hi:[0,1]
	v_pk_add_f32 v[86:87], v[86:87], v[192:193] op_sel:[0,1] op_sel_hi:[1,1] neg_lo:[0,1] neg_hi:[0,1]
	v_exp_f32_e32 v70, v70
	v_exp_f32_e32 v71, v71
	v_exp_f32_e32 v86, v86
	v_exp_f32_e32 v87, v87
	v_pk_add_f32 v[174:175], v[174:175], v[68:69]
	v_pk_add_f32 v[174:175], v[174:175], v[84:85]
	v_pk_add_f32 v[72:73], v[72:73], v[192:193] op_sel:[0,1] op_sel_hi:[1,1] neg_lo:[0,1] neg_hi:[0,1]
	v_pk_add_f32 v[88:89], v[88:89], v[192:193] op_sel:[0,1] op_sel_hi:[1,1] neg_lo:[0,1] neg_hi:[0,1]
	v_exp_f32_e32 v72, v72
	v_exp_f32_e32 v73, v73
	v_exp_f32_e32 v88, v88
	v_exp_f32_e32 v89, v89
	v_pk_add_f32 v[174:175], v[174:175], v[70:71]
	v_pk_add_f32 v[174:175], v[174:175], v[86:87]
	v_pk_add_f32 v[74:75], v[74:75], v[192:193] op_sel:[0,1] op_sel_hi:[1,1] neg_lo:[0,1] neg_hi:[0,1]
	v_pk_add_f32 v[90:91], v[90:91], v[192:193] op_sel:[0,1] op_sel_hi:[1,1] neg_lo:[0,1] neg_hi:[0,1]
	v_exp_f32_e32 v74, v74
	v_exp_f32_e32 v75, v75
	v_exp_f32_e32 v90, v90
	v_exp_f32_e32 v91, v91
	v_pk_add_f32 v[174:175], v[174:175], v[72:73]
	v_pk_add_f32 v[174:175], v[174:175], v[88:89]
	v_pk_add_f32 v[76:77], v[76:77], v[192:193] op_sel:[0,1] op_sel_hi:[1,1] neg_lo:[0,1] neg_hi:[0,1]
	v_pk_add_f32 v[92:93], v[92:93], v[192:193] op_sel:[0,1] op_sel_hi:[1,1] neg_lo:[0,1] neg_hi:[0,1]
	v_exp_f32_e32 v76, v76
	v_exp_f32_e32 v77, v77
	v_exp_f32_e32 v92, v92
	v_exp_f32_e32 v93, v93
	v_pk_add_f32 v[174:175], v[174:175], v[74:75]
	v_pk_add_f32 v[174:175], v[174:175], v[90:91]
	v_pk_add_f32 v[78:79], v[78:79], v[192:193] op_sel:[0,1] op_sel_hi:[1,1] neg_lo:[0,1] neg_hi:[0,1]
	v_pk_add_f32 v[94:95], v[94:95], v[192:193] op_sel:[0,1] op_sel_hi:[1,1] neg_lo:[0,1] neg_hi:[0,1]
	v_exp_f32_e32 v78, v78
	v_exp_f32_e32 v79, v79
	v_exp_f32_e32 v94, v94
	v_exp_f32_e32 v95, v95
	v_pk_add_f32 v[174:175], v[174:175], v[76:77]
	v_pk_add_f32 v[174:175], v[174:175], v[92:93]
	v_pk_add_f32 v[80:81], v[80:81], v[192:193] op_sel:[0,1] op_sel_hi:[1,1] neg_lo:[0,1] neg_hi:[0,1]
	v_pk_add_f32 v[96:97], v[96:97], v[192:193] op_sel:[0,1] op_sel_hi:[1,1] neg_lo:[0,1] neg_hi:[0,1]
	v_exp_f32_e32 v80, v80
	v_exp_f32_e32 v81, v81
	v_exp_f32_e32 v96, v96
	v_exp_f32_e32 v97, v97
	v_pk_add_f32 v[174:175], v[174:175], v[78:79]
	v_pk_add_f32 v[174:175], v[174:175], v[94:95]
	s_nop 0
	v_pk_add_f32 v[174:175], v[174:175], v[80:81]
	v_pk_add_f32 v[174:175], v[174:175], v[96:97]
	v_add_f32_e32 v193, v174, v175
	v_add3_u32 v174, s47, v210, v211
	v_cvt_pk_bf16_f32 v66, v66, v67
	v_cvt_pk_bf16_f32 v67, v68, v69
	v_cvt_pk_bf16_f32 v68, v70, v71
	v_cvt_pk_bf16_f32 v69, v72, v73
	v_cvt_pk_bf16_f32 v70, v74, v75
	v_cvt_pk_bf16_f32 v71, v76, v77
	v_cvt_pk_bf16_f32 v72, v78, v79
	v_cvt_pk_bf16_f32 v73, v80, v81
	v_cvt_pk_bf16_f32 v74, v82, v83
	v_cvt_pk_bf16_f32 v75, v84, v85
	v_cvt_pk_bf16_f32 v76, v86, v87
	v_cvt_pk_bf16_f32 v77, v88, v89
	v_cvt_pk_bf16_f32 v78, v90, v91
	v_cvt_pk_bf16_f32 v79, v92, v93
	v_cvt_pk_bf16_f32 v80, v94, v95
	v_cvt_pk_bf16_f32 v81, v96, v97
	ds_read_b128 v[82:85], v174 offset:17408
	ds_read_b128 v[86:89], v174 offset:22016
	ds_read_b128 v[90:93], v174 offset:26624
	ds_read_b128 v[94:97], v174 offset:31232
	v_fmac_f32_e32 v193, v216, v204
	s_waitcnt lgkmcnt(3)
	v_mfma_f32_32x32x16_bf16 v[50:65], v[82:85], v[66:69], v[50:65]
	s_waitcnt lgkmcnt(2)
	v_mfma_f32_32x32x16_bf16 v[34:49], v[86:89], v[66:69], v[34:49]
	s_waitcnt lgkmcnt(1)
	v_mfma_f32_32x32x16_bf16 v[18:33], v[90:93], v[66:69], v[18:33]
	s_waitcnt lgkmcnt(0)
	v_mfma_f32_32x32x16_bf16 v[2:17], v[94:97], v[66:69], v[2:17]
	ds_read_b128 v[66:69], v174 offset:17440
	ds_read_b128 v[82:85], v174 offset:22048
	ds_read_b128 v[86:89], v174 offset:26656
	ds_read_b128 v[90:93], v174 offset:31264
	s_waitcnt lgkmcnt(3)
	v_mfma_f32_32x32x16_bf16 v[50:65], v[66:69], v[70:73], v[50:65]
	s_waitcnt lgkmcnt(2)
	v_mfma_f32_32x32x16_bf16 v[34:49], v[82:85], v[70:73], v[34:49]
	s_waitcnt lgkmcnt(1)
	v_mfma_f32_32x32x16_bf16 v[18:33], v[86:89], v[70:73], v[18:33]
	s_waitcnt lgkmcnt(0)
	v_mfma_f32_32x32x16_bf16 v[2:17], v[90:93], v[70:73], v[2:17]
	ds_read_b128 v[66:69], v174 offset:17472
	ds_read_b128 v[70:73], v174 offset:22080
	ds_read_b128 v[82:85], v174 offset:26688
	ds_read_b128 v[86:89], v174 offset:31296
	s_waitcnt lgkmcnt(3)
	v_mfma_f32_32x32x16_bf16 v[50:65], v[66:69], v[74:77], v[50:65]
	s_waitcnt lgkmcnt(2)
	v_mfma_f32_32x32x16_bf16 v[34:49], v[70:73], v[74:77], v[34:49]
	s_waitcnt lgkmcnt(1)
	v_mfma_f32_32x32x16_bf16 v[18:33], v[82:85], v[74:77], v[18:33]
	s_waitcnt lgkmcnt(0)
	v_mfma_f32_32x32x16_bf16 v[2:17], v[86:89], v[74:77], v[2:17]
	ds_read_b128 v[66:69], v174 offset:17504
	ds_read_b128 v[70:73], v174 offset:22112
	ds_read_b128 v[74:77], v174 offset:26720
	ds_read_b128 v[82:85], v174 offset:31328
	s_waitcnt lgkmcnt(3)
	v_mfma_f32_32x32x16_bf16 v[50:65], v[66:69], v[78:81], v[50:65]
	s_waitcnt lgkmcnt(2)
	v_mfma_f32_32x32x16_bf16 v[34:49], v[70:73], v[78:81], v[34:49]
	s_waitcnt lgkmcnt(1)
	v_mfma_f32_32x32x16_bf16 v[18:33], v[74:77], v[78:81], v[18:33]
	s_waitcnt lgkmcnt(0)
	v_mfma_f32_32x32x16_bf16 v[2:17], v[82:85], v[78:81], v[2:17]
	v_not_b32_e32 v66, v218
	v_not_b32_e32 v82, v205
	v_bfe_i32 v83, v66, 0, 1
	v_bfe_i32 v174, v82, 0, 1
	v_bfe_i32 v67, v66, 1, 1
	v_bfe_i32 v175, v82, 1, 1
	v_bfe_i32 v68, v66, 2, 1
	v_bfe_i32 v84, v82, 2, 1
	v_bfe_i32 v69, v66, 3, 1
	v_bfe_i32 v85, v82, 3, 1
	v_bfe_i32 v70, v66, 8, 1
	v_bfe_i32 v86, v82, 8, 1
	v_bfe_i32 v71, v66, 9, 1
	v_bfe_i32 v87, v82, 9, 1
	v_bfe_i32 v72, v66, 10, 1
	v_bfe_i32 v88, v82, 10, 1
	v_bfe_i32 v73, v66, 11, 1
	v_bfe_i32 v89, v82, 11, 1
	v_bfe_i32 v74, v66, 16, 1
	v_bfe_i32 v90, v82, 16, 1
	v_bfe_i32 v75, v66, 17, 1
	v_bfe_i32 v91, v82, 17, 1
	v_bfe_i32 v76, v66, 18, 1
	v_bfe_i32 v92, v82, 18, 1
	v_bfe_i32 v77, v66, 19, 1
	v_bfe_i32 v93, v82, 19, 1
	v_bfe_i32 v78, v66, 24, 1
	v_bfe_i32 v94, v82, 24, 1
	v_bfe_i32 v79, v66, 25, 1
	v_bfe_i32 v95, v82, 25, 1
	v_bfe_i32 v80, v66, 26, 1
	v_bfe_i32 v96, v82, 26, 1
	v_bfe_i32 v66, v66, 27, 1
	v_bfe_i32 v82, v82, 27, 1
	s_nop 0
	v_and_b32_e32 v79, 0xff800000, v79
	v_and_b32_e32 v81, 0xff800000, v66
	v_and_b32_e32 v66, 0xff800000, v83
	v_and_b32_e32 v97, 0xff800000, v82
	v_and_b32_e32 v83, 0xff800000, v175
	v_and_b32_e32 v82, 0xff800000, v174
	ds_read_b128 v[174:177], v217 offset:8704
	ds_read_b128 v[218:221], v217
	ds_read_b128 v[222:225], v217 offset:32
	ds_read_b128 v[226:229], v217 offset:8736
	ds_read_b128 v[232:235], v217 offset:64
	ds_read_b128 v[236:239], v217 offset:8768
	ds_read_b128 v[240:243], v217 offset:96
	ds_read_b128 v[248:251], v217 offset:8800
	v_and_b32_e32 v80, 0xff800000, v80
	v_and_b32_e32 v78, 0xff800000, v78
	v_and_b32_e32 v77, 0xff800000, v77
	v_and_b32_e32 v76, 0xff800000, v76
	v_and_b32_e32 v75, 0xff800000, v75
	v_and_b32_e32 v74, 0xff800000, v74
	v_and_b32_e32 v73, 0xff800000, v73
	v_and_b32_e32 v72, 0xff800000, v72
	v_and_b32_e32 v71, 0xff800000, v71
	v_and_b32_e32 v70, 0xff800000, v70
	v_and_b32_e32 v69, 0xff800000, v69
	v_and_b32_e32 v68, 0xff800000, v68
	v_and_b32_e32 v67, 0xff800000, v67
	v_and_b32_e32 v96, 0xff800000, v96
	v_and_b32_e32 v95, 0xff800000, v95
	v_and_b32_e32 v94, 0xff800000, v94
	v_and_b32_e32 v93, 0xff800000, v93
	v_and_b32_e32 v92, 0xff800000, v92
	v_and_b32_e32 v91, 0xff800000, v91
	v_and_b32_e32 v90, 0xff800000, v90
	v_and_b32_e32 v89, 0xff800000, v89
	v_and_b32_e32 v88, 0xff800000, v88
	v_and_b32_e32 v87, 0xff800000, v87
	v_and_b32_e32 v86, 0xff800000, v86
	v_and_b32_e32 v85, 0xff800000, v85
	v_and_b32_e32 v84, 0xff800000, v84
	s_waitcnt lgkmcnt(6)
	v_mfma_f32_32x32x16_bf16 v[66:81], v[218:221], v[98:101], v[66:81]
	v_mfma_f32_32x32x16_bf16 v[82:97], v[174:177], v[98:101], v[82:97]
	s_waitcnt lgkmcnt(5)
	v_mfma_f32_32x32x16_bf16 v[66:81], v[222:225], v[102:105], v[66:81]
	s_waitcnt lgkmcnt(4)
	v_mfma_f32_32x32x16_bf16 v[82:97], v[226:229], v[102:105], v[82:97]
	s_waitcnt lgkmcnt(3)
	v_mfma_f32_32x32x16_bf16 v[66:81], v[232:235], v[106:109], v[66:81]
	s_waitcnt lgkmcnt(2)
	v_mfma_f32_32x32x16_bf16 v[82:97], v[236:239], v[106:109], v[82:97]
	s_waitcnt lgkmcnt(1)
	v_mfma_f32_32x32x16_bf16 v[66:81], v[240:243], v[110:113], v[66:81]
	s_waitcnt lgkmcnt(0)
	v_mfma_f32_32x32x16_bf16 v[82:97], v[248:251], v[110:113], v[82:97]
	ds_read_b128 v[174:177], v217 offset:128
	ds_read_b128 v[218:221], v217 offset:160
	ds_read_b128 v[222:225], v217 offset:8832
	ds_read_b128 v[226:229], v217 offset:8864
	ds_read_b128 v[232:235], v217 offset:192
	ds_read_b128 v[236:239], v217 offset:224
	ds_read_b128 v[240:243], v217 offset:8896
	ds_read_b128 v[248:251], v217 offset:8928
	s_waitcnt lgkmcnt(7)
	v_mfma_f32_32x32x16_bf16 v[66:81], v[174:177], v[114:117], v[66:81]
	s_waitcnt lgkmcnt(5)
	v_mfma_f32_32x32x16_bf16 v[82:97], v[222:225], v[114:117], v[82:97]
	v_mfma_f32_32x32x16_bf16 v[66:81], v[218:221], v[118:121], v[66:81]
	s_waitcnt lgkmcnt(4)
	v_mfma_f32_32x32x16_bf16 v[82:97], v[226:229], v[118:121], v[82:97]
	s_waitcnt lgkmcnt(3)
	v_mfma_f32_32x32x16_bf16 v[66:81], v[232:235], v[122:125], v[66:81]
	s_waitcnt lgkmcnt(1)
	v_mfma_f32_32x32x16_bf16 v[82:97], v[240:243], v[122:125], v[82:97]
	v_mfma_f32_32x32x16_bf16 v[66:81], v[236:239], v[126:129], v[66:81]
	s_waitcnt lgkmcnt(0)
	v_mfma_f32_32x32x16_bf16 v[82:97], v[248:251], v[126:129], v[82:97]
	s_or_b64 exec, exec, s[0:1]
	s_and_b64 vcc, exec, s[8:9]
	s_cbranch_vccz .LBB0_88
	s_branch .LBB0_89
